# conv_weight tiles issue all 8 loads before one wait; write-through stores for converted weights
# speedup vs baseline: 1.0679x; 1.0159x over previous
; template <int MAP>
; DI void conv_weight(float* ldsf, const float* __restrict__ src, u16* __restrict__ dst, const float* __restrict__ gain, int K, int N, int Npad, int bid, int nblk, int wid_k) {
;     ...
;       const int nn = tid & 63; int n = col_map<MAP>(n0 + nn); if (n >= N) n = -1;
; #pragma unroll 4
;       for (int r = 0; r < 8; ++r) {
;         const int kk = r * 8 + (tid >> 6);
;         float v = 0.f;
;         if (n >= 0) { v = __builtin_nontemporal_load(src + (size_t)(k0 + kk) * N + n); if (gain) v *= gain[k0 + kk]; }
;         ldsf[kk * 65 + nn] = v;
;       }
;     }
.LBB0_116:
	s_or_b64 exec, exec, s[16:17]
	s_waitcnt vmcnt(0)
	ds_write_b32 v13, v14
	ds_write_b32 v13, v16 offset:2080
	ds_write_b32 v13, v18 offset:4160
	ds_write_b32 v13, v20 offset:6240
	ds_write_b32 v13, v22 offset:8320
	ds_write_b32 v13, v24 offset:10400
	ds_write_b32 v13, v26 offset:12480
	ds_write_b32 v13, v28 offset:14560
	s_branch .LBB0_104
.LBB0_117:
	v_mov_b32_e32 v14, 0
	v_mov_b32_e32 v16, 0
	v_mov_b32_e32 v18, 0
	v_mov_b32_e32 v20, 0
	v_mov_b32_e32 v22, 0
	v_mov_b32_e32 v24, 0
	v_mov_b32_e32 v26, 0
	v_mov_b32_e32 v28, 0
	s_and_saveexec_b64 s[16:17], vcc
	s_cbranch_execz .LBB0_116
	v_add_u32_e32 v14, s18, v0
	v_mad_i64_i32 v[14:15], s[22:23], v14, s89, v[4:5]
	global_load_dword v14, v[14:15], off nt
	v_add3_u32 v16, v0, s18, 8
	v_mad_i64_i32 v[16:17], s[22:23], v16, s89, v[4:5]
	global_load_dword v16, v[16:17], off nt
	v_add3_u32 v18, v0, s18, 16
	v_mad_i64_i32 v[18:19], s[22:23], v18, s89, v[4:5]
	global_load_dword v18, v[18:19], off nt
	v_add3_u32 v20, v0, s18, 24
	v_mad_i64_i32 v[20:21], s[22:23], v20, s89, v[4:5]
	global_load_dword v20, v[20:21], off nt
	v_add3_u32 v22, v0, s18, 32
	v_mad_i64_i32 v[22:23], s[22:23], v22, s89, v[4:5]
	global_load_dword v22, v[22:23], off nt
	v_add3_u32 v24, v0, s18, 40
	v_mad_i64_i32 v[24:25], s[22:23], v24, s89, v[4:5]
	global_load_dword v24, v[24:25], off nt
	v_add3_u32 v26, v0, s18, 48
	v_mad_i64_i32 v[26:27], s[22:23], v26, s89, v[4:5]
	global_load_dword v26, v[26:27], off nt
	v_add3_u32 v28, v0, s18, 56
	v_mad_i64_i32 v[28:29], s[22:23], v28, s89, v[4:5]
	global_load_dword v28, v[28:29], off nt
	s_branch .LBB0_116

; template <int MAP>
; DI void conv_weight(float* ldsf, const float* __restrict__ src, u16* __restrict__ dst, const float* __restrict__ gain, int K, int N, int Npad, int bid, int nblk, int wid_k) {
;     ...
;       const int nn = tid & 63; int n = col_map<MAP>(n0 + nn); if (n >= N) n = -1;
; #pragma unroll 4
;       for (int r = 0; r < 8; ++r) {
;         const int kk = r * 8 + (tid >> 6);
;         float v = 0.f;
;         if (n >= 0) { v = __builtin_nontemporal_load(src + (size_t)(k0 + kk) * N + n); if (gain) v *= gain[k0 + kk]; }
;         ldsf[kk * 65 + nn] = v;
;       }
;     }
.LBB0_165:
	s_or_b64 exec, exec, s[18:19]
	s_waitcnt vmcnt(0)
	ds_write_b32 v3, v14
	ds_write_b32 v3, v16 offset:2080
	ds_write_b32 v3, v18 offset:4160
	ds_write_b32 v3, v20 offset:6240
	ds_write_b32 v3, v22 offset:8320
	ds_write_b32 v3, v24 offset:10400
	ds_write_b32 v3, v26 offset:12480
	ds_write_b32 v3, v28 offset:14560
	s_branch .LBB0_163
.LBB0_166:
	v_mov_b32_e32 v14, 0
	v_mov_b32_e32 v16, 0
	v_mov_b32_e32 v18, 0
	v_mov_b32_e32 v20, 0
	v_mov_b32_e32 v22, 0
	v_mov_b32_e32 v24, 0
	v_mov_b32_e32 v26, 0
	v_mov_b32_e32 v28, 0
	s_and_saveexec_b64 s[18:19], vcc
	s_cbranch_execz .LBB0_165
	v_add_u32_e32 v14, s22, v0
	v_ashrrev_i32_e32 v15, 31, v14
	v_lshlrev_b64 v[14:15], 12, v[14:15]
	v_lshl_add_u64 v[14:15], v[4:5], 0, v[14:15]
	global_load_dword v14, v[14:15], off nt
	v_add3_u32 v16, v0, s22, 8
	v_ashrrev_i32_e32 v17, 31, v16
	v_lshlrev_b64 v[16:17], 12, v[16:17]
	v_lshl_add_u64 v[16:17], v[4:5], 0, v[16:17]
	global_load_dword v16, v[16:17], off nt
	v_add3_u32 v18, v0, s22, 16
	v_ashrrev_i32_e32 v19, 31, v18
	v_lshlrev_b64 v[18:19], 12, v[18:19]
	v_lshl_add_u64 v[18:19], v[4:5], 0, v[18:19]
	global_load_dword v18, v[18:19], off nt
	v_add3_u32 v20, v0, s22, 24
	v_ashrrev_i32_e32 v21, 31, v20
	v_lshlrev_b64 v[20:21], 12, v[20:21]
	v_lshl_add_u64 v[20:21], v[4:5], 0, v[20:21]
	global_load_dword v20, v[20:21], off nt
	v_add3_u32 v22, v0, s22, 32
	v_ashrrev_i32_e32 v23, 31, v22
	v_lshlrev_b64 v[22:23], 12, v[22:23]
	v_lshl_add_u64 v[22:23], v[4:5], 0, v[22:23]
	global_load_dword v22, v[22:23], off nt
	v_add3_u32 v24, v0, s22, 40
	v_ashrrev_i32_e32 v25, 31, v24
	v_lshlrev_b64 v[24:25], 12, v[24:25]
	v_lshl_add_u64 v[24:25], v[4:5], 0, v[24:25]
	global_load_dword v24, v[24:25], off nt
	v_add3_u32 v26, v0, s22, 48
	v_ashrrev_i32_e32 v27, 31, v26
	v_lshlrev_b64 v[26:27], 12, v[26:27]
	v_lshl_add_u64 v[26:27], v[4:5], 0, v[26:27]
	global_load_dword v26, v[26:27], off nt
	v_add3_u32 v28, v0, s22, 56
	v_ashrrev_i32_e32 v29, 31, v28
	v_lshlrev_b64 v[28:29], 12, v[28:29]
	v_lshl_add_u64 v[28:29], v[4:5], 0, v[28:29]
	global_load_dword v28, v[28:29], off nt
	s_branch .LBB0_165

; template <int MAP>
; DI void conv_weight(float* ldsf, const float* __restrict__ src, u16* __restrict__ dst, const float* __restrict__ gain, int K, int N, int Npad, int bid, int nblk, int wid_k) {
;     ...
;       const int nn = tid & 63; int n = col_map<MAP>(n0 + nn); if (n >= N) n = -1;
; #pragma unroll 4
;       for (int r = 0; r < 8; ++r) {
;         const int kk = r * 8 + (tid >> 6);
;         float v = 0.f;
;         if (n >= 0) { v = __builtin_nontemporal_load(src + (size_t)(k0 + kk) * N + n); if (gain) v *= gain[k0 + kk]; }
;         ldsf[kk * 65 + nn] = v;
;       }
;     }
.LBB0_178:
	s_or_b64 exec, exec, s[16:17]
	s_waitcnt vmcnt(0)
	ds_write_b32 v3, v14
	ds_write_b32 v3, v16 offset:2080
	ds_write_b32 v3, v18 offset:4160
	ds_write_b32 v3, v20 offset:6240
	ds_write_b32 v3, v22 offset:8320
	ds_write_b32 v3, v24 offset:10400
	ds_write_b32 v3, v26 offset:12480
	ds_write_b32 v3, v28 offset:14560
	s_branch .LBB0_176
.LBB0_179:
	v_mov_b32_e32 v14, 0
	v_mov_b32_e32 v16, 0
	v_mov_b32_e32 v18, 0
	v_mov_b32_e32 v20, 0
	v_mov_b32_e32 v22, 0
	v_mov_b32_e32 v24, 0
	v_mov_b32_e32 v26, 0
	v_mov_b32_e32 v28, 0
	s_and_saveexec_b64 s[16:17], vcc
	s_cbranch_execz .LBB0_178
	v_add_u32_e32 v14, s20, v0
	v_ashrrev_i32_e32 v15, 31, v14
	v_lshlrev_b64 v[14:15], 12, v[14:15]
	v_lshl_add_u64 v[14:15], v[4:5], 0, v[14:15]
	global_load_dword v14, v[14:15], off nt
	v_add3_u32 v16, v0, s20, 8
	v_ashrrev_i32_e32 v17, 31, v16
	v_lshlrev_b64 v[16:17], 12, v[16:17]
	v_lshl_add_u64 v[16:17], v[4:5], 0, v[16:17]
	global_load_dword v16, v[16:17], off nt
	v_add3_u32 v18, v0, s20, 16
	v_ashrrev_i32_e32 v19, 31, v18
	v_lshlrev_b64 v[18:19], 12, v[18:19]
	v_lshl_add_u64 v[18:19], v[4:5], 0, v[18:19]
	global_load_dword v18, v[18:19], off nt
	v_add3_u32 v20, v0, s20, 24
	v_ashrrev_i32_e32 v21, 31, v20
	v_lshlrev_b64 v[20:21], 12, v[20:21]
	v_lshl_add_u64 v[20:21], v[4:5], 0, v[20:21]
	global_load_dword v20, v[20:21], off nt
	v_add3_u32 v22, v0, s20, 32
	v_ashrrev_i32_e32 v23, 31, v22
	v_lshlrev_b64 v[22:23], 12, v[22:23]
	v_lshl_add_u64 v[22:23], v[4:5], 0, v[22:23]
	global_load_dword v22, v[22:23], off nt
	v_add3_u32 v24, v0, s20, 40
	v_ashrrev_i32_e32 v25, 31, v24
	v_lshlrev_b64 v[24:25], 12, v[24:25]
	v_lshl_add_u64 v[24:25], v[4:5], 0, v[24:25]
	global_load_dword v24, v[24:25], off nt
	v_add3_u32 v26, v0, s20, 48
	v_ashrrev_i32_e32 v27, 31, v26
	v_lshlrev_b64 v[26:27], 12, v[26:27]
	v_lshl_add_u64 v[26:27], v[4:5], 0, v[26:27]
	global_load_dword v26, v[26:27], off nt
	v_add3_u32 v28, v0, s20, 56
	v_ashrrev_i32_e32 v29, 31, v28
	v_lshlrev_b64 v[28:29], 12, v[28:29]
	v_lshl_add_u64 v[28:29], v[4:5], 0, v[28:29]
	global_load_dword v28, v[28:29], off nt
	s_branch .LBB0_178

; template <int MAP>
; DI void conv_weight(float* ldsf, const float* __restrict__ src, u16* __restrict__ dst, const float* __restrict__ gain, int K, int N, int Npad, int bid, int nblk, int wid_k) {
;     ...
;       const int nn = tid & 63; int n = col_map<MAP>(n0 + nn); if (n >= N) n = -1;
; #pragma unroll 4
;       for (int r = 0; r < 8; ++r) {
;         const int kk = r * 8 + (tid >> 6);
;         float v = 0.f;
;         if (n >= 0) { v = __builtin_nontemporal_load(src + (size_t)(k0 + kk) * N + n); if (gain) v *= gain[k0 + kk]; }
;         ldsf[kk * 65 + nn] = v;
;       }
;     }
.LBB0_218:
	v_mov_b32_e32 v14, 0
	v_mov_b32_e32 v16, 0
	v_mov_b32_e32 v18, 0
	v_mov_b32_e32 v20, 0
	v_mov_b32_e32 v22, 0
	v_mov_b32_e32 v24, 0
	v_mov_b32_e32 v26, 0
	v_mov_b32_e32 v28, 0
	s_and_saveexec_b64 s[18:19], vcc
	s_cbranch_execz .LBB0_217
	v_add_u32_e32 v14, s22, v0
	v_ashrrev_i32_e32 v15, 31, v14
	v_lshlrev_b64 v[14:15], 14, v[14:15]
	v_lshl_add_u64 v[14:15], v[4:5], 0, v[14:15]
	global_load_dword v14, v[14:15], off nt
	v_add3_u32 v16, v0, s22, 8
	v_ashrrev_i32_e32 v17, 31, v16
	v_lshlrev_b64 v[16:17], 14, v[16:17]
	v_lshl_add_u64 v[16:17], v[4:5], 0, v[16:17]
	global_load_dword v16, v[16:17], off nt
	v_add3_u32 v18, v0, s22, 16
	v_ashrrev_i32_e32 v19, 31, v18
	v_lshlrev_b64 v[18:19], 14, v[18:19]
	v_lshl_add_u64 v[18:19], v[4:5], 0, v[18:19]
	global_load_dword v18, v[18:19], off nt
	v_add3_u32 v20, v0, s22, 24
	v_ashrrev_i32_e32 v21, 31, v20
	v_lshlrev_b64 v[20:21], 14, v[20:21]
	v_lshl_add_u64 v[20:21], v[4:5], 0, v[20:21]
	global_load_dword v20, v[20:21], off nt
	v_add3_u32 v22, v0, s22, 32
	v_ashrrev_i32_e32 v23, 31, v22
	v_lshlrev_b64 v[22:23], 14, v[22:23]
	v_lshl_add_u64 v[22:23], v[4:5], 0, v[22:23]
	global_load_dword v22, v[22:23], off nt
	v_add3_u32 v24, v0, s22, 40
	v_ashrrev_i32_e32 v25, 31, v24
	v_lshlrev_b64 v[24:25], 14, v[24:25]
	v_lshl_add_u64 v[24:25], v[4:5], 0, v[24:25]
	global_load_dword v24, v[24:25], off nt
	v_add3_u32 v26, v0, s22, 48
	v_ashrrev_i32_e32 v27, 31, v26
	v_lshlrev_b64 v[26:27], 14, v[26:27]
	v_lshl_add_u64 v[26:27], v[4:5], 0, v[26:27]
	global_load_dword v26, v[26:27], off nt
	v_add3_u32 v28, v0, s22, 56
	v_ashrrev_i32_e32 v29, 31, v28
	v_lshlrev_b64 v[28:29], 14, v[28:29]
	v_lshl_add_u64 v[28:29], v[4:5], 0, v[28:29]
	global_load_dword v28, v[28:29], off nt
	s_branch .LBB0_217

; DI unsigned pack2(float a, float b) { f32v2 v = {a, b}; bf16v2 r = __builtin_convertvector(v, bf16v2); return __builtin_bit_cast(unsigned, r); }
; template <int MAP>
; DI void conv_weight(float* ldsf, const float* __restrict__ src, u16* __restrict__ dst, const float* __restrict__ gain, int K, int N, int Npad, int bid, int nblk, int wid_k) {
;     ...
;     __syncthreads();
;     {
;       const int nn = tid >> 3, kb = (tid & 7) * 8;
;       uint4 o;
;       o.x = pack2(ldsf[(kb + 0) * 65 + nn], ldsf[(kb + 1) * 65 + nn]); o.y = pack2(ldsf[(kb + 2) * 65 + nn], ldsf[(kb + 3) * 65 + nn]);
;       o.z = pack2(ldsf[(kb + 4) * 65 + nn], ldsf[(kb + 5) * 65 + nn]); o.w = pack2(ldsf[(kb + 6) * 65 + nn], ldsf[(kb + 7) * 65 + nn]);
;       *(uint4*)(dst + (size_t)(n0 + nn) * K + k0 + kb) = o;
;     }
.LBB0_1375:
	s_waitcnt lgkmcnt(0)
	s_barrier
	ds_read2_b32 v[4:5], v9 offset1:65
	v_add_u32_e32 v0, 0x400, v9
	s_lshl_b32 s6, s18, 4
	s_sub_i32 s6, s16, s6
	s_lshl_b32 s6, s6, 6
	s_waitcnt lgkmcnt(0)
	v_cvt_pk_bf16_f32 v12, v4, v5
	ds_read2_b32 v[4:5], v9 offset0:130 offset1:195
	s_ashr_i32 s7, s6, 31
	v_mov_b32_e32 v3, v1
	s_add_i32 s16, s16, s62
	s_cmpk_gt_i32 s16, 0x57f
	s_waitcnt lgkmcnt(0)
	v_cvt_pk_bf16_f32 v13, v4, v5
	ds_read2_b32 v[4:5], v0 offset0:4 offset1:69
	s_waitcnt lgkmcnt(0)
	v_cvt_pk_bf16_f32 v14, v4, v5
	ds_read2_b32 v[4:5], v0 offset0:134 offset1:199
	s_waitcnt lgkmcnt(0)
	v_cvt_pk_bf16_f32 v15, v4, v5
	v_add_u32_e32 v4, s17, v8
	v_ashrrev_i32_e32 v5, 31, v4
	v_lshlrev_b64 v[4:5], 11, v[4:5]
	v_lshl_add_u64 v[4:5], s[4:5], 0, v[4:5]
	v_lshl_add_u64 v[4:5], s[6:7], 1, v[4:5]
	v_lshl_add_u64 v[4:5], v[4:5], 0, v[2:3]
	global_store_dwordx4 v[4:5], v[12:15], off sc1
	s_cbranch_scc1 .LBB0_1396

; template <int MAP>
; DI void conv_weight(float* ldsf, const float* __restrict__ src, u16* __restrict__ dst, const float* __restrict__ gain, int K, int N, int Npad, int bid, int nblk, int wid_k) {
;     ...
;       const int nn = tid & 63; int n = col_map<MAP>(n0 + nn); if (n >= N) n = -1;
; #pragma unroll 4
;       for (int r = 0; r < 8; ++r) {
;         const int kk = r * 8 + (tid >> 6);
;         float v = 0.f;
;         if (n >= 0) { v = __builtin_nontemporal_load(src + (size_t)(k0 + kk) * N + n); if (gain) v *= gain[k0 + kk]; }
;         ldsf[kk * 65 + nn] = v;
;       }
;     }
.LBB0_1387:
	s_or_b64 exec, exec, s[6:7]
	s_waitcnt vmcnt(0)
	ds_write_b32 v3, v12
	ds_write_b32 v3, v14 offset:2080
	ds_write_b32 v3, v16 offset:4160
	ds_write_b32 v3, v18 offset:6240
	ds_write_b32 v3, v20 offset:8320
	ds_write_b32 v3, v22 offset:10400
	ds_write_b32 v3, v24 offset:12480
	ds_write_b32 v3, v26 offset:14560
	s_branch .LBB0_1375
.LBB0_1388:
	v_mov_b32_e32 v12, 0
	v_mov_b32_e32 v14, 0
	v_mov_b32_e32 v16, 0
	v_mov_b32_e32 v18, 0
	v_mov_b32_e32 v20, 0
	v_mov_b32_e32 v22, 0
	v_mov_b32_e32 v24, 0
	v_mov_b32_e32 v26, 0
	s_and_saveexec_b64 s[6:7], vcc
	s_cbranch_execz .LBB0_1387
	v_add_u32_e32 v12, s14, v0
	v_mad_i64_i32 v[12:13], s[20:21], v12, s89, v[4:5]
	global_load_dword v12, v[12:13], off nt
	v_add3_u32 v14, v0, s14, 8
	v_mad_i64_i32 v[14:15], s[20:21], v14, s89, v[4:5]
	global_load_dword v14, v[14:15], off nt
	v_add3_u32 v16, v0, s14, 16
	v_mad_i64_i32 v[16:17], s[20:21], v16, s89, v[4:5]
	global_load_dword v16, v[16:17], off nt
	v_add3_u32 v18, v0, s14, 24
	v_mad_i64_i32 v[18:19], s[20:21], v18, s89, v[4:5]
	global_load_dword v18, v[18:19], off nt
	v_add3_u32 v20, v0, s14, 32
	v_mad_i64_i32 v[20:21], s[20:21], v20, s89, v[4:5]
	global_load_dword v20, v[20:21], off nt
	v_add3_u32 v22, v0, s14, 40
	v_mad_i64_i32 v[22:23], s[20:21], v22, s89, v[4:5]
	global_load_dword v22, v[22:23], off nt
	v_add3_u32 v24, v0, s14, 48
	v_mad_i64_i32 v[24:25], s[20:21], v24, s89, v[4:5]
	global_load_dword v24, v[24:25], off nt
	v_add3_u32 v26, v0, s14, 56
	v_mad_i64_i32 v[26:27], s[20:21], v26, s89, v[4:5]
	global_load_dword v26, v[26:27], off nt
	s_branch .LBB0_1387

; DI unsigned pack2(float a, float b) { f32v2 v = {a, b}; bf16v2 r = __builtin_convertvector(v, bf16v2); return __builtin_bit_cast(unsigned, r); }
; template <int MAP>
; DI void conv_weight(float* ldsf, const float* __restrict__ src, u16* __restrict__ dst, const float* __restrict__ gain, int K, int N, int Npad, int bid, int nblk, int wid_k) {
;     ...
;     __syncthreads();
;     {
;       const int nn = tid >> 3, kb = (tid & 7) * 8;
;       uint4 o;
;       o.x = pack2(ldsf[(kb + 0) * 65 + nn], ldsf[(kb + 1) * 65 + nn]); o.y = pack2(ldsf[(kb + 2) * 65 + nn], ldsf[(kb + 3) * 65 + nn]);
;       o.z = pack2(ldsf[(kb + 4) * 65 + nn], ldsf[(kb + 5) * 65 + nn]); o.w = pack2(ldsf[(kb + 6) * 65 + nn], ldsf[(kb + 7) * 65 + nn]);
;       *(uint4*)(dst + (size_t)(n0 + nn) * K + k0 + kb) = o;
;     }
.LBB0_1398:
	s_waitcnt lgkmcnt(0)
	s_barrier
	ds_read2_b32 v[6:7], v14 offset1:65
	ds_read2_b32 v[8:9], v14 offset0:130 offset1:195
	v_add_u32_e32 v0, 0x400, v14
	ds_read2_b32 v[10:11], v0 offset0:134 offset1:199
	v_mov_b32_e32 v5, v1
	s_waitcnt lgkmcnt(2)
	v_cvt_pk_bf16_f32 v6, v6, v7
	s_waitcnt lgkmcnt(1)
	v_cvt_pk_bf16_f32 v7, v8, v9
	ds_read2_b32 v[8:9], v0 offset0:4 offset1:69
	v_add_u32_e32 v0, s23, v13
	s_add_i32 s22, s22, s62
	s_cmpk_gt_i32 s22, 0x47
	s_waitcnt lgkmcnt(0)
	v_cvt_pk_bf16_f32 v8, v8, v9
	v_cvt_pk_bf16_f32 v9, v10, v11
	v_mov_b64_e32 v[10:11], s[6:7]
	v_mad_i64_i32 v[10:11], s[18:19], v0, s1, v[10:11]
	v_lshl_add_u64 v[10:11], s[16:17], 1, v[10:11]
	v_lshl_add_u64 v[10:11], v[10:11], 0, v[4:5]
	global_store_dwordx4 v[10:11], v[6:9], off sc1
	s_cbranch_scc1 .LBB0_1411

; DI unsigned pack2(float a, float b) { f32v2 v = {a, b}; bf16v2 r = __builtin_convertvector(v, bf16v2); return __builtin_bit_cast(unsigned, r); }
; template <int MAP>
; DI void conv_weight(float* ldsf, const float* __restrict__ src, u16* __restrict__ dst, const float* __restrict__ gain, int K, int N, int Npad, int bid, int nblk, int wid_k) {
;     ...
;     __syncthreads();
;     {
;       const int nn = tid >> 3, kb = (tid & 7) * 8;
;       uint4 o;
;       o.x = pack2(ldsf[(kb + 0) * 65 + nn], ldsf[(kb + 1) * 65 + nn]); o.y = pack2(ldsf[(kb + 2) * 65 + nn], ldsf[(kb + 3) * 65 + nn]);
;       o.z = pack2(ldsf[(kb + 4) * 65 + nn], ldsf[(kb + 5) * 65 + nn]); o.w = pack2(ldsf[(kb + 6) * 65 + nn], ldsf[(kb + 7) * 65 + nn]);
;       *(uint4*)(dst + (size_t)(n0 + nn) * K + k0 + kb) = o;
;     }
.LBB0_1413:
	s_waitcnt lgkmcnt(0)
	s_barrier
	ds_read2_b32 v[6:7], v14 offset1:65
	ds_read2_b32 v[8:9], v14 offset0:130 offset1:195
	v_add_u32_e32 v0, 0x400, v14
	ds_read2_b32 v[10:11], v0 offset0:134 offset1:199
	v_mov_b32_e32 v5, v1
	s_waitcnt lgkmcnt(2)
	v_cvt_pk_bf16_f32 v6, v6, v7
	s_waitcnt lgkmcnt(1)
	v_cvt_pk_bf16_f32 v7, v8, v9
	ds_read2_b32 v[8:9], v0 offset0:4 offset1:69
	s_add_i32 s29, s29, s62
	s_cmp_gt_i32 s29, 63
	s_waitcnt lgkmcnt(0)
	v_cvt_pk_bf16_f32 v8, v8, v9
	v_cvt_pk_bf16_f32 v9, v10, v11
	v_add_u32_e32 v10, s30, v13
	v_ashrrev_i32_e32 v11, 31, v10
	v_lshlrev_b64 v[10:11], 9, v[10:11]
	v_lshl_add_u64 v[10:11], s[6:7], 0, v[10:11]
	v_lshl_add_u64 v[10:11], s[20:21], 1, v[10:11]
	v_lshl_add_u64 v[10:11], v[10:11], 0, v[4:5]
	global_store_dwordx4 v[10:11], v[6:9], off sc1
	s_cbranch_scc1 .LBB0_1424

; DI unsigned pack2(float a, float b) { f32v2 v = {a, b}; bf16v2 r = __builtin_convertvector(v, bf16v2); return __builtin_bit_cast(unsigned, r); }
; template <int MAP>
; DI void conv_weight(float* ldsf, const float* __restrict__ src, u16* __restrict__ dst, const float* __restrict__ gain, int K, int N, int Npad, int bid, int nblk, int wid_k) {
;     ...
;     __syncthreads();
;     {
;       const int nn = tid >> 3, kb = (tid & 7) * 8;
;       uint4 o;
;       o.x = pack2(ldsf[(kb + 0) * 65 + nn], ldsf[(kb + 1) * 65 + nn]); o.y = pack2(ldsf[(kb + 2) * 65 + nn], ldsf[(kb + 3) * 65 + nn]);
;       o.z = pack2(ldsf[(kb + 4) * 65 + nn], ldsf[(kb + 5) * 65 + nn]); o.w = pack2(ldsf[(kb + 6) * 65 + nn], ldsf[(kb + 7) * 65 + nn]);
;       *(uint4*)(dst + (size_t)(n0 + nn) * K + k0 + kb) = o;
;     }
.LBB0_1426:
	s_waitcnt lgkmcnt(0)
	s_barrier
	ds_read2_b32 v[4:5], v9 offset1:65
	v_add_u32_e32 v0, 0x400, v9
	s_lshl_b32 s16, s20, 2
	s_sub_i32 s16, s18, s16
	s_lshl_b32 s16, s16, 6
	s_waitcnt lgkmcnt(0)
	v_cvt_pk_bf16_f32 v12, v4, v5
	ds_read2_b32 v[4:5], v9 offset0:130 offset1:195
	s_ashr_i32 s17, s16, 31
	v_mov_b32_e32 v3, v1
	s_add_i32 s18, s18, s62
	s_cmp_gt_i32 s18, 63
	s_waitcnt lgkmcnt(0)
	v_cvt_pk_bf16_f32 v13, v4, v5
	ds_read2_b32 v[4:5], v0 offset0:4 offset1:69
	s_waitcnt lgkmcnt(0)
	v_cvt_pk_bf16_f32 v14, v4, v5
	ds_read2_b32 v[4:5], v0 offset0:134 offset1:199
	s_waitcnt lgkmcnt(0)
	v_cvt_pk_bf16_f32 v15, v4, v5
	v_add_u32_e32 v4, s19, v8
	v_ashrrev_i32_e32 v5, 31, v4
	v_lshlrev_b64 v[4:5], 9, v[4:5]
	v_lshl_add_u64 v[4:5], s[6:7], 0, v[4:5]
	v_lshl_add_u64 v[4:5], s[16:17], 1, v[4:5]
	v_lshl_add_u64 v[4:5], v[4:5], 0, v[2:3]
	global_store_dwordx4 v[4:5], v[12:15], off sc1
	s_cbranch_scc1 .LBB0_1437

; template <int MAP>
; DI void conv_weight(float* ldsf, const float* __restrict__ src, u16* __restrict__ dst, const float* __restrict__ gain, int K, int N, int Npad, int bid, int nblk, int wid_k) {
;     ...
;       const int nn = tid & 63; int n = col_map<MAP>(n0 + nn); if (n >= N) n = -1;
; #pragma unroll 4
;       for (int r = 0; r < 8; ++r) {
;         const int kk = r * 8 + (tid >> 6);
;         float v = 0.f;
;         if (n >= 0) { v = __builtin_nontemporal_load(src + (size_t)(k0 + kk) * N + n); if (gain) v *= gain[k0 + kk]; }
;         ldsf[kk * 65 + nn] = v;
;       }
;     }
.LBB0_1428:
	s_or_b64 exec, exec, s[16:17]
	s_waitcnt vmcnt(0)
	ds_write_b32 v3, v12
	ds_write_b32 v3, v14 offset:2080
	ds_write_b32 v3, v16 offset:4160
	ds_write_b32 v3, v18 offset:6240
	ds_write_b32 v3, v20 offset:8320
	ds_write_b32 v3, v22 offset:10400
	ds_write_b32 v3, v24 offset:12480
	ds_write_b32 v3, v26 offset:14560
	s_branch .LBB0_1426
.LBB0_1429:
	v_mov_b32_e32 v12, 0
	v_mov_b32_e32 v14, 0
	v_mov_b32_e32 v16, 0
	v_mov_b32_e32 v18, 0
	v_mov_b32_e32 v20, 0
	v_mov_b32_e32 v22, 0
	v_mov_b32_e32 v24, 0
	v_mov_b32_e32 v26, 0
	s_and_saveexec_b64 s[16:17], vcc
	s_cbranch_execz .LBB0_1428
	v_add_u32_e32 v12, s21, v0
	v_ashrrev_i32_e32 v13, 31, v12
	v_lshlrev_b64 v[12:13], 12, v[12:13]
	v_lshl_add_u64 v[12:13], v[4:5], 0, v[12:13]
	global_load_dword v12, v[12:13], off nt
	v_add3_u32 v14, v0, s21, 8
	v_ashrrev_i32_e32 v15, 31, v14
	v_lshlrev_b64 v[14:15], 12, v[14:15]
	v_lshl_add_u64 v[14:15], v[4:5], 0, v[14:15]
	global_load_dword v14, v[14:15], off nt
	v_add3_u32 v16, v0, s21, 16
	v_ashrrev_i32_e32 v17, 31, v16
	v_lshlrev_b64 v[16:17], 12, v[16:17]
	v_lshl_add_u64 v[16:17], v[4:5], 0, v[16:17]
	global_load_dword v16, v[16:17], off nt
	v_add3_u32 v18, v0, s21, 24
	v_ashrrev_i32_e32 v19, 31, v18
	v_lshlrev_b64 v[18:19], 12, v[18:19]
	v_lshl_add_u64 v[18:19], v[4:5], 0, v[18:19]
	global_load_dword v18, v[18:19], off nt
	v_add3_u32 v20, v0, s21, 32
	v_ashrrev_i32_e32 v21, 31, v20
	v_lshlrev_b64 v[20:21], 12, v[20:21]
	v_lshl_add_u64 v[20:21], v[4:5], 0, v[20:21]
	global_load_dword v20, v[20:21], off nt
	v_add3_u32 v22, v0, s21, 40
	v_ashrrev_i32_e32 v23, 31, v22
	v_lshlrev_b64 v[22:23], 12, v[22:23]
	v_lshl_add_u64 v[22:23], v[4:5], 0, v[22:23]
	global_load_dword v22, v[22:23], off nt
	v_add3_u32 v24, v0, s21, 48
	v_ashrrev_i32_e32 v25, 31, v24
	v_lshlrev_b64 v[24:25], 12, v[24:25]
	v_lshl_add_u64 v[24:25], v[4:5], 0, v[24:25]
	global_load_dword v24, v[24:25], off nt
	v_add3_u32 v26, v0, s21, 56
	v_ashrrev_i32_e32 v27, 31, v26
	v_lshlrev_b64 v[26:27], 12, v[26:27]
	v_lshl_add_u64 v[26:27], v[4:5], 0, v[26:27]
	global_load_dword v26, v[26:27], off nt
	s_branch .LBB0_1428

; DI unsigned pack2(float a, float b) { f32v2 v = {a, b}; bf16v2 r = __builtin_convertvector(v, bf16v2); return __builtin_bit_cast(unsigned, r); }
; template <int MAP>
; DI void conv_weight(float* ldsf, const float* __restrict__ src, u16* __restrict__ dst, const float* __restrict__ gain, int K, int N, int Npad, int bid, int nblk, int wid_k) {
;     ...
;     __syncthreads();
;     {
;       const int nn = tid >> 3, kb = (tid & 7) * 8;
;       uint4 o;
;       o.x = pack2(ldsf[(kb + 0) * 65 + nn], ldsf[(kb + 1) * 65 + nn]); o.y = pack2(ldsf[(kb + 2) * 65 + nn], ldsf[(kb + 3) * 65 + nn]);
;       o.z = pack2(ldsf[(kb + 4) * 65 + nn], ldsf[(kb + 5) * 65 + nn]); o.w = pack2(ldsf[(kb + 6) * 65 + nn], ldsf[(kb + 7) * 65 + nn]);
;       *(uint4*)(dst + (size_t)(n0 + nn) * K + k0 + kb) = o;
;     }
.LBB0_1439:
	s_waitcnt lgkmcnt(0)
	s_barrier
	ds_read2_b32 v[4:5], v9 offset1:65
	v_add_u32_e32 v0, 0x400, v9
	s_lshl_b32 s6, s16, 2
	s_sub_i32 s6, s14, s6
	s_lshl_b32 s6, s6, 6
	s_waitcnt lgkmcnt(0)
	v_cvt_pk_bf16_f32 v12, v4, v5
	ds_read2_b32 v[4:5], v9 offset0:130 offset1:195
	s_ashr_i32 s7, s6, 31
	v_mov_b32_e32 v3, v1
	s_add_i32 s14, s14, s62
	s_cmp_gt_i32 s14, 63
	s_waitcnt lgkmcnt(0)
	v_cvt_pk_bf16_f32 v13, v4, v5
	ds_read2_b32 v[4:5], v0 offset0:4 offset1:69
	s_waitcnt lgkmcnt(0)
	v_cvt_pk_bf16_f32 v14, v4, v5
	ds_read2_b32 v[4:5], v0 offset0:134 offset1:199
	s_waitcnt lgkmcnt(0)
	v_cvt_pk_bf16_f32 v15, v4, v5
	v_add_u32_e32 v4, s15, v8
	v_ashrrev_i32_e32 v5, 31, v4
	v_lshlrev_b64 v[4:5], 9, v[4:5]
	v_lshl_add_u64 v[4:5], s[4:5], 0, v[4:5]
	v_lshl_add_u64 v[4:5], s[6:7], 1, v[4:5]
	v_lshl_add_u64 v[4:5], v[4:5], 0, v[2:3]
	global_store_dwordx4 v[4:5], v[12:15], off sc1
	s_cbranch_scc1 .LBB0_1450

; template <int MAP>
; DI void conv_weight(float* ldsf, const float* __restrict__ src, u16* __restrict__ dst, const float* __restrict__ gain, int K, int N, int Npad, int bid, int nblk, int wid_k) {
;     ...
;       const int nn = tid & 63; int n = col_map<MAP>(n0 + nn); if (n >= N) n = -1;
; #pragma unroll 4
;       for (int r = 0; r < 8; ++r) {
;         const int kk = r * 8 + (tid >> 6);
;         float v = 0.f;
;         if (n >= 0) { v = __builtin_nontemporal_load(src + (size_t)(k0 + kk) * N + n); if (gain) v *= gain[k0 + kk]; }
;         ldsf[kk * 65 + nn] = v;
;       }
;     }
.LBB0_1442:
	v_mov_b32_e32 v12, 0
	v_mov_b32_e32 v14, 0
	v_mov_b32_e32 v16, 0
	v_mov_b32_e32 v18, 0
	v_mov_b32_e32 v20, 0
	v_mov_b32_e32 v22, 0
	v_mov_b32_e32 v24, 0
	v_mov_b32_e32 v26, 0
	s_and_saveexec_b64 s[6:7], vcc
	s_cbranch_execz .LBB0_1441
	v_add_u32_e32 v12, s17, v0
	v_ashrrev_i32_e32 v13, 31, v12
	v_lshlrev_b64 v[12:13], 12, v[12:13]
	v_lshl_add_u64 v[12:13], v[4:5], 0, v[12:13]
	global_load_dword v12, v[12:13], off nt
	v_add3_u32 v14, v0, s17, 8
	v_ashrrev_i32_e32 v15, 31, v14
	v_lshlrev_b64 v[14:15], 12, v[14:15]
	v_lshl_add_u64 v[14:15], v[4:5], 0, v[14:15]
	global_load_dword v14, v[14:15], off nt
	v_add3_u32 v16, v0, s17, 16
	v_ashrrev_i32_e32 v17, 31, v16
	v_lshlrev_b64 v[16:17], 12, v[16:17]
	v_lshl_add_u64 v[16:17], v[4:5], 0, v[16:17]
	global_load_dword v16, v[16:17], off nt
	v_add3_u32 v18, v0, s17, 24
	v_ashrrev_i32_e32 v19, 31, v18
	v_lshlrev_b64 v[18:19], 12, v[18:19]
	v_lshl_add_u64 v[18:19], v[4:5], 0, v[18:19]
	global_load_dword v18, v[18:19], off nt
	v_add3_u32 v20, v0, s17, 32
	v_ashrrev_i32_e32 v21, 31, v20
	v_lshlrev_b64 v[20:21], 12, v[20:21]
	v_lshl_add_u64 v[20:21], v[4:5], 0, v[20:21]
	global_load_dword v20, v[20:21], off nt
	v_add3_u32 v22, v0, s17, 40
	v_ashrrev_i32_e32 v23, 31, v22
	v_lshlrev_b64 v[22:23], 12, v[22:23]
	v_lshl_add_u64 v[22:23], v[4:5], 0, v[22:23]
	global_load_dword v22, v[22:23], off nt
	v_add3_u32 v24, v0, s17, 48
	v_ashrrev_i32_e32 v25, 31, v24
	v_lshlrev_b64 v[24:25], 12, v[24:25]
	v_lshl_add_u64 v[24:25], v[4:5], 0, v[24:25]
	global_load_dword v24, v[24:25], off nt
	v_add3_u32 v26, v0, s17, 56
	v_ashrrev_i32_e32 v27, 31, v26
	v_lshlrev_b64 v[26:27], 12, v[26:27]
	v_lshl_add_u64 v[26:27], v[4:5], 0, v[26:27]
	global_load_dword v26, v[26:27], off nt
	s_branch .LBB0_1441

; DI unsigned pack2(float a, float b) { f32v2 v = {a, b}; bf16v2 r = __builtin_convertvector(v, bf16v2); return __builtin_bit_cast(unsigned, r); }
; template <int MAP>
; DI void conv_weight(float* ldsf, const float* __restrict__ src, u16* __restrict__ dst, const float* __restrict__ gain, int K, int N, int Npad, int bid, int nblk, int wid_k) {
;     ...
;     __syncthreads();
;     {
;       const int nn = tid >> 3, kb = (tid & 7) * 8;
;       uint4 o;
;       o.x = pack2(ldsf[(kb + 0) * 65 + nn], ldsf[(kb + 1) * 65 + nn]); o.y = pack2(ldsf[(kb + 2) * 65 + nn], ldsf[(kb + 3) * 65 + nn]);
;       o.z = pack2(ldsf[(kb + 4) * 65 + nn], ldsf[(kb + 5) * 65 + nn]); o.w = pack2(ldsf[(kb + 6) * 65 + nn], ldsf[(kb + 7) * 65 + nn]);
;       *(uint4*)(dst + (size_t)(n0 + nn) * K + k0 + kb) = o;
;     }
.LBB0_1452:
	s_waitcnt lgkmcnt(0)
	s_barrier
	ds_read2_b32 v[4:5], v9 offset1:65
	v_add_u32_e32 v0, 0x400, v9
	s_lshl_b32 s6, s16, 3
	s_sub_i32 s6, s14, s6
	s_lshl_b32 s6, s6, 6
	s_waitcnt lgkmcnt(0)
	v_cvt_pk_bf16_f32 v12, v4, v5
	ds_read2_b32 v[4:5], v9 offset0:130 offset1:195
	s_ashr_i32 s7, s6, 31
	v_mov_b32_e32 v3, v1
	s_add_i32 s14, s14, s62
	s_cmpk_gt_i32 s14, 0x7f
	s_waitcnt lgkmcnt(0)
	v_cvt_pk_bf16_f32 v13, v4, v5
	ds_read2_b32 v[4:5], v0 offset0:4 offset1:69
	s_waitcnt lgkmcnt(0)
	v_cvt_pk_bf16_f32 v14, v4, v5
	ds_read2_b32 v[4:5], v0 offset0:134 offset1:199
	s_waitcnt lgkmcnt(0)
	v_cvt_pk_bf16_f32 v15, v4, v5
	v_add_u32_e32 v4, s15, v8
	v_ashrrev_i32_e32 v5, 31, v4
	v_lshlrev_b64 v[4:5], 10, v[4:5]
	v_lshl_add_u64 v[4:5], s[4:5], 0, v[4:5]
	v_lshl_add_u64 v[4:5], s[6:7], 1, v[4:5]
	v_lshl_add_u64 v[4:5], v[4:5], 0, v[2:3]
	global_store_dwordx4 v[4:5], v[12:15], off sc1
	s_cbranch_scc1 .LBB0_1463

; DI unsigned pack2(float a, float b) { f32v2 v = {a, b}; bf16v2 r = __builtin_convertvector(v, bf16v2); return __builtin_bit_cast(unsigned, r); }
; template <int MAP>
; DI void conv_weight(float* ldsf, const float* __restrict__ src, u16* __restrict__ dst, const float* __restrict__ gain, int K, int N, int Npad, int bid, int nblk, int wid_k) {
;     ...
;     __syncthreads();
;     {
;       const int nn = tid >> 3, kb = (tid & 7) * 8;
;       uint4 o;
;       o.x = pack2(ldsf[(kb + 0) * 65 + nn], ldsf[(kb + 1) * 65 + nn]); o.y = pack2(ldsf[(kb + 2) * 65 + nn], ldsf[(kb + 3) * 65 + nn]);
;       o.z = pack2(ldsf[(kb + 4) * 65 + nn], ldsf[(kb + 5) * 65 + nn]); o.w = pack2(ldsf[(kb + 6) * 65 + nn], ldsf[(kb + 7) * 65 + nn]);
;       *(uint4*)(dst + (size_t)(n0 + nn) * K + k0 + kb) = o;
;     }
.LBB0_1465:
	s_waitcnt lgkmcnt(0)
	s_barrier
	ds_read2_b32 v[4:5], v9 offset1:65
	v_add_u32_e32 v0, 0x400, v9
	s_lshl_b32 s6, s16, 4
	s_sub_i32 s6, s14, s6
	s_lshl_b32 s6, s6, 6
	s_waitcnt lgkmcnt(0)
	v_cvt_pk_bf16_f32 v12, v4, v5
	ds_read2_b32 v[4:5], v9 offset0:130 offset1:195
	s_ashr_i32 s7, s6, 31
	v_mov_b32_e32 v3, v1
	s_add_i32 s14, s14, s62
	s_cmpk_gt_i32 s14, 0xff
	s_waitcnt lgkmcnt(0)
	v_cvt_pk_bf16_f32 v13, v4, v5
	ds_read2_b32 v[4:5], v0 offset0:4 offset1:69
	s_waitcnt lgkmcnt(0)
	v_cvt_pk_bf16_f32 v14, v4, v5
	ds_read2_b32 v[4:5], v0 offset0:134 offset1:199
	s_waitcnt lgkmcnt(0)
	v_cvt_pk_bf16_f32 v15, v4, v5
	v_add_u32_e32 v4, s15, v8
	v_ashrrev_i32_e32 v5, 31, v4
	v_lshlrev_b64 v[4:5], 11, v[4:5]
	v_lshl_add_u64 v[4:5], s[4:5], 0, v[4:5]
	v_lshl_add_u64 v[4:5], s[6:7], 1, v[4:5]
	v_lshl_add_u64 v[4:5], v[4:5], 0, v[2:3]
	global_store_dwordx4 v[4:5], v[12:15], off sc1
	s_cbranch_scc1 .LBB0_1476

; DI unsigned pack2(float a, float b) { f32v2 v = {a, b}; bf16v2 r = __builtin_convertvector(v, bf16v2); return __builtin_bit_cast(unsigned, r); }
; template <int MAP>
; DI void conv_weight(float* ldsf, const float* __restrict__ src, u16* __restrict__ dst, const float* __restrict__ gain, int K, int N, int Npad, int bid, int nblk, int wid_k) {
;     ...
;     __syncthreads();
;     {
;       const int nn = tid >> 3, kb = (tid & 7) * 8;
;       uint4 o;
;       o.x = pack2(ldsf[(kb + 0) * 65 + nn], ldsf[(kb + 1) * 65 + nn]); o.y = pack2(ldsf[(kb + 2) * 65 + nn], ldsf[(kb + 3) * 65 + nn]);
;       o.z = pack2(ldsf[(kb + 4) * 65 + nn], ldsf[(kb + 5) * 65 + nn]); o.w = pack2(ldsf[(kb + 6) * 65 + nn], ldsf[(kb + 7) * 65 + nn]);
;       *(uint4*)(dst + (size_t)(n0 + nn) * K + k0 + kb) = o;
;     }
.LBB0_1478:
	s_waitcnt lgkmcnt(0)
	s_barrier
	ds_read2_b32 v[4:5], v9 offset1:65
	v_add_u32_e32 v0, 0x400, v9
	s_lshl_b32 s16, s20, 4
	s_sub_i32 s16, s18, s16
	s_lshl_b32 s16, s16, 6
	s_waitcnt lgkmcnt(0)
	v_cvt_pk_bf16_f32 v12, v4, v5
	ds_read2_b32 v[4:5], v9 offset0:130 offset1:195
	s_ashr_i32 s17, s16, 31
	v_mov_b32_e32 v3, v1
	s_add_i32 s18, s18, s62
	s_cmpk_gt_i32 s18, 0x3ff
	s_waitcnt lgkmcnt(0)
	v_cvt_pk_bf16_f32 v13, v4, v5
	ds_read2_b32 v[4:5], v0 offset0:4 offset1:69
	s_waitcnt lgkmcnt(0)
	v_cvt_pk_bf16_f32 v14, v4, v5
	ds_read2_b32 v[4:5], v0 offset0:134 offset1:199
	s_waitcnt lgkmcnt(0)
	v_cvt_pk_bf16_f32 v15, v4, v5
	v_add_u32_e32 v4, s19, v8
	v_ashrrev_i32_e32 v5, 31, v4
	v_lshlrev_b64 v[4:5], 11, v[4:5]
	v_lshl_add_u64 v[4:5], s[14:15], 0, v[4:5]
	v_lshl_add_u64 v[4:5], s[16:17], 1, v[4:5]
	v_lshl_add_u64 v[4:5], v[4:5], 0, v[2:3]
	global_store_dwordx4 v[4:5], v[12:15], off sc1
	s_cbranch_scc1 .LBB0_1489

; template <int MAP>
; DI void conv_weight(float* ldsf, const float* __restrict__ src, u16* __restrict__ dst, const float* __restrict__ gain, int K, int N, int Npad, int bid, int nblk, int wid_k) {
;     ...
;       const int nn = tid & 63; int n = col_map<MAP>(n0 + nn); if (n >= N) n = -1;
; #pragma unroll 4
;       for (int r = 0; r < 8; ++r) {
;         const int kk = r * 8 + (tid >> 6);
;         float v = 0.f;
;         if (n >= 0) { v = __builtin_nontemporal_load(src + (size_t)(k0 + kk) * N + n); if (gain) v *= gain[k0 + kk]; }
;         ldsf[kk * 65 + nn] = v;
;       }
;     }
.LBB0_1481:
	v_mov_b32_e32 v12, 0
	v_mov_b32_e32 v14, 0
	v_mov_b32_e32 v16, 0
	v_mov_b32_e32 v18, 0
	v_mov_b32_e32 v20, 0
	v_mov_b32_e32 v22, 0
	v_mov_b32_e32 v24, 0
	v_mov_b32_e32 v26, 0
	s_and_saveexec_b64 s[16:17], vcc
	s_cbranch_execz .LBB0_1480
	v_add_u32_e32 v12, s21, v0
	v_ashrrev_i32_e32 v13, 31, v12
	v_lshlrev_b64 v[12:13], 14, v[12:13]
	v_lshl_add_u64 v[12:13], v[4:5], 0, v[12:13]
	global_load_dword v12, v[12:13], off nt
	v_add3_u32 v14, v0, s21, 8
	v_ashrrev_i32_e32 v15, 31, v14
	v_lshlrev_b64 v[14:15], 14, v[14:15]
	v_lshl_add_u64 v[14:15], v[4:5], 0, v[14:15]
	global_load_dword v14, v[14:15], off nt
	v_add3_u32 v16, v0, s21, 16
	v_ashrrev_i32_e32 v17, 31, v16
	v_lshlrev_b64 v[16:17], 14, v[16:17]
	v_lshl_add_u64 v[16:17], v[4:5], 0, v[16:17]
	global_load_dword v16, v[16:17], off nt
	v_add3_u32 v18, v0, s21, 24
	v_ashrrev_i32_e32 v19, 31, v18
	v_lshlrev_b64 v[18:19], 14, v[18:19]
	v_lshl_add_u64 v[18:19], v[4:5], 0, v[18:19]
	global_load_dword v18, v[18:19], off nt
	v_add3_u32 v20, v0, s21, 32
	v_ashrrev_i32_e32 v21, 31, v20
	v_lshlrev_b64 v[20:21], 14, v[20:21]
	v_lshl_add_u64 v[20:21], v[4:5], 0, v[20:21]
	global_load_dword v20, v[20:21], off nt
	v_add3_u32 v22, v0, s21, 40
	v_ashrrev_i32_e32 v23, 31, v22
	v_lshlrev_b64 v[22:23], 14, v[22:23]
	v_lshl_add_u64 v[22:23], v[4:5], 0, v[22:23]
	global_load_dword v22, v[22:23], off nt
	v_add3_u32 v24, v0, s21, 48
	v_ashrrev_i32_e32 v25, 31, v24
	v_lshlrev_b64 v[24:25], 14, v[24:25]
	v_lshl_add_u64 v[24:25], v[4:5], 0, v[24:25]
	global_load_dword v24, v[24:25], off nt
	v_add3_u32 v26, v0, s21, 56
	v_ashrrev_i32_e32 v27, 31, v26
	v_lshlrev_b64 v[26:27], 14, v[26:27]
	v_lshl_add_u64 v[26:27], v[4:5], 0, v[26:27]
	global_load_dword v26, v[26:27], off nt
	s_branch .LBB0_1480

; DI unsigned pack2(float a, float b) { f32v2 v = {a, b}; bf16v2 r = __builtin_convertvector(v, bf16v2); return __builtin_bit_cast(unsigned, r); }
; template <int MAP>
; DI void conv_weight(float* ldsf, const float* __restrict__ src, u16* __restrict__ dst, const float* __restrict__ gain, int K, int N, int Npad, int bid, int nblk, int wid_k) {
;     ...
;     __syncthreads();
;     {
;       const int nn = tid >> 3, kb = (tid & 7) * 8;
;       uint4 o;
;       o.x = pack2(ldsf[(kb + 0) * 65 + nn], ldsf[(kb + 1) * 65 + nn]); o.y = pack2(ldsf[(kb + 2) * 65 + nn], ldsf[(kb + 3) * 65 + nn]);
;       o.z = pack2(ldsf[(kb + 4) * 65 + nn], ldsf[(kb + 5) * 65 + nn]); o.w = pack2(ldsf[(kb + 6) * 65 + nn], ldsf[(kb + 7) * 65 + nn]);
;       *(uint4*)(dst + (size_t)(n0 + nn) * K + k0 + kb) = o;
;     }
.LBB0_1491:
	s_waitcnt lgkmcnt(0)
	s_barrier
	ds_read2_b32 v[4:5], v9 offset1:65
	v_add_u32_e32 v0, 0x400, v9
	s_lshl_b32 s6, s16, 6
	s_sub_i32 s6, s14, s6
	s_lshl_b32 s6, s6, 6
	s_waitcnt lgkmcnt(0)
	v_cvt_pk_bf16_f32 v12, v4, v5
	ds_read2_b32 v[4:5], v9 offset0:130 offset1:195
	s_ashr_i32 s7, s6, 31
	v_mov_b32_e32 v3, v1
	s_add_i32 s14, s14, s62
	s_cmpk_gt_i32 s14, 0x3ff
	s_waitcnt lgkmcnt(0)
	v_cvt_pk_bf16_f32 v13, v4, v5
	ds_read2_b32 v[4:5], v0 offset0:4 offset1:69
	s_waitcnt lgkmcnt(0)
	v_cvt_pk_bf16_f32 v14, v4, v5
	ds_read2_b32 v[4:5], v0 offset0:134 offset1:199
	s_waitcnt lgkmcnt(0)
	v_cvt_pk_bf16_f32 v15, v4, v5
	v_add_u32_e32 v4, s15, v8
	v_ashrrev_i32_e32 v5, 31, v4
	v_lshlrev_b64 v[4:5], 13, v[4:5]
	v_lshl_add_u64 v[4:5], s[4:5], 0, v[4:5]
	v_lshl_add_u64 v[4:5], s[6:7], 1, v[4:5]
	v_lshl_add_u64 v[4:5], v[4:5], 0, v[2:3]
	global_store_dwordx4 v[4:5], v[12:15], off sc1
	s_cbranch_scc1 .LBB0_1502
